# grid barrier: L1 invalidate (acquire) issued before polling for the release instead of after it (only sc1 polls run in between)
# speedup vs baseline: 1.0054x; 1.0041x over previous
; __device__ __forceinline__ unsigned xb_ld(unsigned* p)              { return __hip_atomic_load(p, __ATOMIC_RELAXED, __HIP_MEMORY_SCOPE_AGENT); }
; __device__ __forceinline__ unsigned xb_add(unsigned* p, unsigned v) { return __hip_atomic_fetch_add(p, v, __ATOMIC_RELAXED, __HIP_MEMORY_SCOPE_AGENT); }
; #define XB_SPIN(cond, bar) do { unsigned _sp = 0; while (cond) { __builtin_amdgcn_s_sleep(1); \
;     if ((++_sp & 255u) == 0u) { if (xb_ld(&(bar)[XB_TMO])) break; if (_sp > XB_SPIN_CAP) { atomicAdd(&(bar)[XB_TMO], 1u); break; } } } } while (0)
; __device__ __forceinline__ void xcd_barrier(const XcdBarrier& b) {
;     ...
;         const unsigned old = xb_add(&bar[XB_XSUB(b.x)], 1u);
;         const unsigned gen = old / nloc;
;         if (old + 1u == (gen + 1u) * nloc) {
;             __builtin_amdgcn_fence(__ATOMIC_RELEASE, "agent");
;             asm volatile("s_waitcnt vmcnt(0)" ::: "memory");
;             const unsigned og = xb_add(&bar[XB_TOP], 1u);
;             const unsigned tg = og / nx;
;             if (og + 1u == (tg + 1u) * nx) xb_add(&bar[XB_TOPGEN], 1u);
;             else XB_SPIN(xb_ld(&bar[XB_TOPGEN]) == tg, bar);
;             __builtin_amdgcn_fence(__ATOMIC_ACQUIRE, "agent");
.LBB0_236:
	s_or_b64 exec, exec, s[8:9]
	v_cvt_f32_u32_e32 v4, v2
	s_waitcnt vmcnt(0)
	v_readfirstlane_b32 s6, v3
	v_sub_u32_e32 v3, 0, v2
	v_rcp_iflag_f32_e32 v4, v4
	v_add_u32_e32 v5, s6, v1
	v_mul_f32_e32 v4, 0x4f7ffffe, v4
	v_cvt_u32_f32_e32 v4, v4
	v_mul_lo_u32 v1, v3, v4
	v_mul_hi_u32 v1, v4, v1
	v_add_u32_e32 v1, v4, v1
	v_mul_hi_u32 v1, v5, v1
	v_mul_lo_u32 v3, v1, v2
	v_sub_u32_e32 v3, v5, v3
	v_add_u32_e32 v4, 1, v1
	v_cmp_ge_u32_e32 vcc, v3, v2
	s_nop 1
	v_cndmask_b32_e32 v1, v1, v4, vcc
	v_sub_u32_e32 v4, v3, v2
	v_cndmask_b32_e32 v3, v3, v4, vcc
	v_add_u32_e32 v4, 1, v1
	v_cmp_ge_u32_e32 vcc, v3, v2
	v_add_u32_e32 v3, 1, v5
	s_nop 0
	v_cndmask_b32_e32 v1, v1, v4, vcc
	v_mul_lo_u32 v4, v2, v1
	v_add_u32_e32 v2, v4, v2
	v_cmp_ne_u32_e32 vcc, v3, v2
	s_and_saveexec_b64 s[6:7], vcc
	s_xor_b64 s[6:7], exec, s[6:7]
	s_cbranch_execz .LBB0_250
	s_waitcnt lgkmcnt(0)
	v_mov_b32_e32 v0, 0
	s_add_u32 s12, s88, 0x803500
	s_addc_u32 s13, s89, 0
	buffer_inv sc1
	global_load_dword v0, v0, s[12:13] sc1
	s_waitcnt vmcnt(0)
	v_cmp_eq_u32_e32 vcc, v0, v1
	s_and_saveexec_b64 s[8:9], vcc
	s_cbranch_execz .LBB0_249
	s_add_u32 s10, s88, 0x800200
	s_addc_u32 s11, s89, 0
	s_mov_b32 s33, 1
	s_mov_b64 s[14:15], 0
	v_mov_b32_e32 v0, 0
	s_branch .LBB0_240

; __device__ __forceinline__ unsigned xb_ld(unsigned* p)              { return __hip_atomic_load(p, __ATOMIC_RELAXED, __HIP_MEMORY_SCOPE_AGENT); }
; __device__ __forceinline__ unsigned xb_add(unsigned* p, unsigned v) { return __hip_atomic_fetch_add(p, v, __ATOMIC_RELAXED, __HIP_MEMORY_SCOPE_AGENT); }
; #define XB_SPIN(cond, bar) do { unsigned _sp = 0; while (cond) { __builtin_amdgcn_s_sleep(1); \
;     if ((++_sp & 255u) == 0u) { if (xb_ld(&(bar)[XB_TMO])) break; if (_sp > XB_SPIN_CAP) { atomicAdd(&(bar)[XB_TMO], 1u); break; } } } } while (0)
; __device__ __forceinline__ void xcd_barrier(const XcdBarrier& b) {
;     ...
;             else XB_SPIN(xb_ld(&bar[XB_TOPGEN]) == tg, bar);
;             __builtin_amdgcn_fence(__ATOMIC_ACQUIRE, "agent");
;             xb_add(&bar[XB_XGEN(b.x)], 1u);
;             asm volatile("s_waitcnt vmcnt(0)" ::: "memory");
.LBB0_249:
	s_or_b64 exec, exec, s[8:9]
	s_waitcnt vmcnt(0)
	s_waitcnt vmcnt(0)

; __device__ __forceinline__ unsigned xb_ld(unsigned* p)              { return __hip_atomic_load(p, __ATOMIC_RELAXED, __HIP_MEMORY_SCOPE_AGENT); }
; __device__ __forceinline__ unsigned xb_add(unsigned* p, unsigned v) { return __hip_atomic_fetch_add(p, v, __ATOMIC_RELAXED, __HIP_MEMORY_SCOPE_AGENT); }
; #define XB_SPIN(cond, bar) do { unsigned _sp = 0; while (cond) { __builtin_amdgcn_s_sleep(1); \
;     if ((++_sp & 255u) == 0u) { if (xb_ld(&(bar)[XB_TMO])) break; if (_sp > XB_SPIN_CAP) { atomicAdd(&(bar)[XB_TMO], 1u); break; } } } } while (0)
; __device__ __forceinline__ void xcd_barrier(const XcdBarrier& b) {
;     ...
;         const unsigned old = xb_add(&bar[XB_XSUB(b.x)], 1u);
;         const unsigned gen = old / nloc;
;         if (old + 1u == (gen + 1u) * nloc) {
;             __builtin_amdgcn_fence(__ATOMIC_RELEASE, "agent");
;             asm volatile("s_waitcnt vmcnt(0)" ::: "memory");
;             const unsigned og = xb_add(&bar[XB_TOP], 1u);
;             const unsigned tg = og / nx;
;             if (og + 1u == (tg + 1u) * nx) xb_add(&bar[XB_TOPGEN], 1u);
;             else XB_SPIN(xb_ld(&bar[XB_TOPGEN]) == tg, bar);
;             __builtin_amdgcn_fence(__ATOMIC_ACQUIRE, "agent");
.LBB0_253:
	s_or_b64 exec, exec, s[8:9]
	buffer_inv sc1
	v_cvt_f32_u32_e32 v3, v0
	s_waitcnt vmcnt(0)
	v_readfirstlane_b32 s6, v2
	s_add_u32 s8, s88, 0x803500
	s_addc_u32 s9, s89, 0
	v_rcp_iflag_f32_e32 v3, v3
	v_add_u32_e32 v1, s6, v1
	v_add_u32_e32 v4, 1, v1
	s_mov_b64 s[10:11], -1
	v_mul_f32_e32 v2, 0x4f7ffffe, v3
	v_cvt_u32_f32_e32 v2, v2
	v_sub_u32_e32 v3, 0, v0
	v_mul_lo_u32 v3, v3, v2
	v_mul_hi_u32 v3, v2, v3
	v_add_u32_e32 v2, v2, v3
	v_mul_hi_u32 v2, v1, v2
	v_mul_lo_u32 v3, v2, v0
	v_sub_u32_e32 v1, v1, v3
	v_add_u32_e32 v5, 1, v2
	v_cmp_ge_u32_e32 vcc, v1, v0
	v_sub_u32_e32 v3, v1, v0
	s_nop 0
	v_cndmask_b32_e32 v2, v2, v5, vcc
	v_cndmask_b32_e32 v1, v1, v3, vcc
	v_add_u32_e32 v3, 1, v2
	v_cmp_ge_u32_e32 vcc, v1, v0
	s_nop 1
	v_cndmask_b32_e32 v2, v2, v3, vcc
	v_mul_lo_u32 v1, v0, v2
	v_add_u32_e32 v0, v1, v0
	v_cmp_ne_u32_e32 vcc, v4, v0
	v_mov_b64_e32 v[0:1], s[8:9]
	s_and_saveexec_b64 s[6:7], vcc
	s_cbranch_execz .LBB0_265
	v_mov_b32_e32 v0, 0
	global_load_dword v1, v0, s[8:9] sc1
	s_mov_b64 s[14:15], 0
	s_waitcnt vmcnt(0)
	v_cmp_eq_u32_e32 vcc, v1, v2
	s_and_saveexec_b64 s[12:13], vcc
	s_cbranch_execz .LBB0_264
	s_add_u32 s10, s88, 0x800200
	s_addc_u32 s11, s89, 0
	s_mov_b32 s33, 1
	s_branch .LBB0_257

; __device__ __forceinline__ unsigned xb_add(unsigned* p, unsigned v) { return __hip_atomic_fetch_add(p, v, __ATOMIC_RELAXED, __HIP_MEMORY_SCOPE_AGENT); }
; __device__ __forceinline__ void xcd_barrier(const XcdBarrier& b) {
;     ...
;             __builtin_amdgcn_fence(__ATOMIC_ACQUIRE, "agent");
;             xb_add(&bar[XB_XGEN(b.x)], 1u);
;             asm volatile("s_waitcnt vmcnt(0)" ::: "memory");
.LBB0_267:
	s_or_b64 exec, exec, s[6:7]
	s_mov_b64 s[6:7], exec
	v_mbcnt_lo_u32_b32 v0, s6, 0
	v_mbcnt_hi_u32_b32 v0, s7, v0
	v_cmp_eq_u32_e32 vcc, 0, v0
	s_waitcnt vmcnt(0)
	s_and_saveexec_b64 s[8:9], vcc
	s_cbranch_execz .LBB0_269
	s_bcnt1_i32_b64 s6, s[6:7]
	v_mov_b32_e32 v0, 0x2000
	v_mov_b32_e32 v1, s6

; __device__ __forceinline__ unsigned xb_ld(unsigned* p)              { return __hip_atomic_load(p, __ATOMIC_RELAXED, __HIP_MEMORY_SCOPE_AGENT); }
; __device__ __forceinline__ unsigned xb_add(unsigned* p, unsigned v) { return __hip_atomic_fetch_add(p, v, __ATOMIC_RELAXED, __HIP_MEMORY_SCOPE_AGENT); }
; #define XB_SPIN(cond, bar) do { unsigned _sp = 0; while (cond) { __builtin_amdgcn_s_sleep(1); \
;     if ((++_sp & 255u) == 0u) { if (xb_ld(&(bar)[XB_TMO])) break; if (_sp > XB_SPIN_CAP) { atomicAdd(&(bar)[XB_TMO], 1u); break; } } } } while (0)
; __device__ __forceinline__ void xcd_barrier(const XcdBarrier& b) {
;     ...
;         const unsigned old = xb_add(&bar[XB_XSUB(b.x)], 1u);
;         const unsigned gen = old / nloc;
;         if (old + 1u == (gen + 1u) * nloc) {
;             __builtin_amdgcn_fence(__ATOMIC_RELEASE, "agent");
;             asm volatile("s_waitcnt vmcnt(0)" ::: "memory");
;             const unsigned og = xb_add(&bar[XB_TOP], 1u);
;             const unsigned tg = og / nx;
;             if (og + 1u == (tg + 1u) * nx) xb_add(&bar[XB_TOPGEN], 1u);
;             else XB_SPIN(xb_ld(&bar[XB_TOPGEN]) == tg, bar);
;             __builtin_amdgcn_fence(__ATOMIC_ACQUIRE, "agent");
.LBB0_525:
	s_or_b64 exec, exec, s[8:9]
	v_cvt_f32_u32_e32 v4, v2
	s_waitcnt vmcnt(0)
	v_readfirstlane_b32 s6, v3
	v_sub_u32_e32 v3, 0, v2
	v_rcp_iflag_f32_e32 v4, v4
	v_add_u32_e32 v5, s6, v1
	v_mul_f32_e32 v4, 0x4f7ffffe, v4
	v_cvt_u32_f32_e32 v4, v4
	v_mul_lo_u32 v1, v3, v4
	v_mul_hi_u32 v1, v4, v1
	v_add_u32_e32 v1, v4, v1
	v_mul_hi_u32 v1, v5, v1
	v_mul_lo_u32 v3, v1, v2
	v_sub_u32_e32 v3, v5, v3
	v_add_u32_e32 v4, 1, v1
	v_cmp_ge_u32_e32 vcc, v3, v2
	s_nop 1
	v_cndmask_b32_e32 v1, v1, v4, vcc
	v_sub_u32_e32 v4, v3, v2
	v_cndmask_b32_e32 v3, v3, v4, vcc
	v_add_u32_e32 v4, 1, v1
	v_cmp_ge_u32_e32 vcc, v3, v2
	v_add_u32_e32 v3, 1, v5
	s_nop 0
	v_cndmask_b32_e32 v1, v1, v4, vcc
	v_mul_lo_u32 v4, v2, v1
	v_add_u32_e32 v2, v4, v2
	v_cmp_ne_u32_e32 vcc, v3, v2
	s_and_saveexec_b64 s[6:7], vcc
	s_xor_b64 s[6:7], exec, s[6:7]
	s_cbranch_execz .LBB0_539
	s_waitcnt lgkmcnt(0)
	v_mov_b32_e32 v0, 0
	s_add_u32 s14, s88, 0x803500
	s_addc_u32 s15, s89, 0
	buffer_inv sc1
	global_load_dword v0, v0, s[14:15] sc1
	s_waitcnt vmcnt(0)
	v_cmp_eq_u32_e32 vcc, v0, v1
	s_and_saveexec_b64 s[8:9], vcc
	s_cbranch_execz .LBB0_538
	s_add_u32 s10, s88, 0x800200
	s_addc_u32 s11, s89, 0
	s_mov_b32 s33, 1
	s_mov_b64 s[16:17], 0
	v_mov_b32_e32 v0, 0
	s_branch .LBB0_529

; __device__ __forceinline__ unsigned xb_ld(unsigned* p)              { return __hip_atomic_load(p, __ATOMIC_RELAXED, __HIP_MEMORY_SCOPE_AGENT); }
; __device__ __forceinline__ unsigned xb_add(unsigned* p, unsigned v) { return __hip_atomic_fetch_add(p, v, __ATOMIC_RELAXED, __HIP_MEMORY_SCOPE_AGENT); }
; #define XB_SPIN(cond, bar) do { unsigned _sp = 0; while (cond) { __builtin_amdgcn_s_sleep(1); \
;     if ((++_sp & 255u) == 0u) { if (xb_ld(&(bar)[XB_TMO])) break; if (_sp > XB_SPIN_CAP) { atomicAdd(&(bar)[XB_TMO], 1u); break; } } } } while (0)
; __device__ __forceinline__ void xcd_barrier(const XcdBarrier& b) {
;     ...
;         const unsigned old = xb_add(&bar[XB_XSUB(b.x)], 1u);
;         const unsigned gen = old / nloc;
;         if (old + 1u == (gen + 1u) * nloc) {
;             __builtin_amdgcn_fence(__ATOMIC_RELEASE, "agent");
;             asm volatile("s_waitcnt vmcnt(0)" ::: "memory");
;             const unsigned og = xb_add(&bar[XB_TOP], 1u);
;             const unsigned tg = og / nx;
;             if (og + 1u == (tg + 1u) * nx) xb_add(&bar[XB_TOPGEN], 1u);
;             else XB_SPIN(xb_ld(&bar[XB_TOPGEN]) == tg, bar);
;             __builtin_amdgcn_fence(__ATOMIC_ACQUIRE, "agent");
.LBB0_542:
	s_or_b64 exec, exec, s[8:9]
	buffer_inv sc1
	v_cvt_f32_u32_e32 v3, v0
	s_waitcnt vmcnt(0)
	v_readfirstlane_b32 s6, v2
	s_add_u32 s8, s88, 0x803500
	s_addc_u32 s9, s89, 0
	v_rcp_iflag_f32_e32 v3, v3
	v_add_u32_e32 v1, s6, v1
	v_add_u32_e32 v4, 1, v1
	s_mov_b64 s[10:11], -1
	v_mul_f32_e32 v2, 0x4f7ffffe, v3
	v_cvt_u32_f32_e32 v2, v2
	v_sub_u32_e32 v3, 0, v0
	v_mul_lo_u32 v3, v3, v2
	v_mul_hi_u32 v3, v2, v3
	v_add_u32_e32 v2, v2, v3
	v_mul_hi_u32 v2, v1, v2
	v_mul_lo_u32 v3, v2, v0
	v_sub_u32_e32 v1, v1, v3
	v_add_u32_e32 v5, 1, v2
	v_cmp_ge_u32_e32 vcc, v1, v0
	v_sub_u32_e32 v3, v1, v0
	s_nop 0
	v_cndmask_b32_e32 v2, v2, v5, vcc
	v_cndmask_b32_e32 v1, v1, v3, vcc
	v_add_u32_e32 v3, 1, v2
	v_cmp_ge_u32_e32 vcc, v1, v0
	s_nop 1
	v_cndmask_b32_e32 v2, v2, v3, vcc
	v_mul_lo_u32 v1, v0, v2
	v_add_u32_e32 v0, v1, v0
	v_cmp_ne_u32_e32 vcc, v4, v0
	v_mov_b64_e32 v[0:1], s[8:9]
	s_and_saveexec_b64 s[6:7], vcc
	s_cbranch_execz .LBB0_554
	v_mov_b32_e32 v0, 0
	global_load_dword v1, v0, s[8:9] sc1
	s_mov_b64 s[16:17], 0
	s_waitcnt vmcnt(0)
	v_cmp_eq_u32_e32 vcc, v1, v2
	s_and_saveexec_b64 s[14:15], vcc
	s_cbranch_execz .LBB0_553
	s_add_u32 s10, s88, 0x800200
	s_addc_u32 s11, s89, 0
	s_mov_b32 s33, 1
	s_branch .LBB0_546

; __device__ __forceinline__ unsigned xb_ld(unsigned* p)              { return __hip_atomic_load(p, __ATOMIC_RELAXED, __HIP_MEMORY_SCOPE_AGENT); }
; __device__ __forceinline__ unsigned xb_add(unsigned* p, unsigned v) { return __hip_atomic_fetch_add(p, v, __ATOMIC_RELAXED, __HIP_MEMORY_SCOPE_AGENT); }
; #define XB_SPIN(cond, bar) do { unsigned _sp = 0; while (cond) { __builtin_amdgcn_s_sleep(1); \
;     if ((++_sp & 255u) == 0u) { if (xb_ld(&(bar)[XB_TMO])) break; if (_sp > XB_SPIN_CAP) { atomicAdd(&(bar)[XB_TMO], 1u); break; } } } } while (0)
; __device__ __forceinline__ void xcd_barrier(const XcdBarrier& b) {
;     ...
;         const unsigned old = xb_add(&bar[XB_XSUB(b.x)], 1u);
;         const unsigned gen = old / nloc;
;         if (old + 1u == (gen + 1u) * nloc) {
;             __builtin_amdgcn_fence(__ATOMIC_RELEASE, "agent");
;             asm volatile("s_waitcnt vmcnt(0)" ::: "memory");
;             const unsigned og = xb_add(&bar[XB_TOP], 1u);
;             const unsigned tg = og / nx;
;             if (og + 1u == (tg + 1u) * nx) xb_add(&bar[XB_TOPGEN], 1u);
;             else XB_SPIN(xb_ld(&bar[XB_TOPGEN]) == tg, bar);
;             __builtin_amdgcn_fence(__ATOMIC_ACQUIRE, "agent");
.LBB0_618:
	s_or_b64 exec, exec, s[10:11]
	v_cvt_f32_u32_e32 v4, v2
	s_waitcnt vmcnt(0)
	v_readfirstlane_b32 s2, v3
	v_sub_u32_e32 v3, 0, v2
	v_rcp_iflag_f32_e32 v4, v4
	v_add_u32_e32 v5, s2, v1
	v_mul_f32_e32 v4, 0x4f7ffffe, v4
	v_cvt_u32_f32_e32 v4, v4
	v_mul_lo_u32 v1, v3, v4
	v_mul_hi_u32 v1, v4, v1
	v_add_u32_e32 v1, v4, v1
	v_mul_hi_u32 v1, v5, v1
	v_mul_lo_u32 v3, v1, v2
	v_sub_u32_e32 v3, v5, v3
	v_add_u32_e32 v4, 1, v1
	v_cmp_ge_u32_e32 vcc, v3, v2
	s_nop 1
	v_cndmask_b32_e32 v1, v1, v4, vcc
	v_sub_u32_e32 v4, v3, v2
	v_cndmask_b32_e32 v3, v3, v4, vcc
	v_add_u32_e32 v4, 1, v1
	v_cmp_ge_u32_e32 vcc, v3, v2
	v_add_u32_e32 v3, 1, v5
	s_nop 0
	v_cndmask_b32_e32 v1, v1, v4, vcc
	v_mul_lo_u32 v4, v2, v1
	v_add_u32_e32 v2, v4, v2
	v_cmp_ne_u32_e32 vcc, v3, v2
	s_and_saveexec_b64 s[2:3], vcc
	s_xor_b64 s[8:9], exec, s[2:3]
	s_cbranch_execz .LBB0_632
	s_waitcnt lgkmcnt(0)
	v_mov_b32_e32 v0, 0
	s_add_u32 s14, s88, 0x803500
	s_addc_u32 s15, s89, 0
	buffer_inv sc1
	global_load_dword v0, v0, s[14:15] sc1
	s_waitcnt vmcnt(0)
	v_cmp_eq_u32_e32 vcc, v0, v1
	s_and_saveexec_b64 s[10:11], vcc
	s_cbranch_execz .LBB0_631
	s_add_u32 s12, s88, 0x800200
	s_addc_u32 s13, s89, 0
	s_mov_b32 s2, 1
	s_mov_b64 s[16:17], 0
	v_mov_b32_e32 v0, 0
	s_branch .LBB0_622

; __device__ __forceinline__ unsigned xb_ld(unsigned* p)              { return __hip_atomic_load(p, __ATOMIC_RELAXED, __HIP_MEMORY_SCOPE_AGENT); }
; __device__ __forceinline__ unsigned xb_add(unsigned* p, unsigned v) { return __hip_atomic_fetch_add(p, v, __ATOMIC_RELAXED, __HIP_MEMORY_SCOPE_AGENT); }
; #define XB_SPIN(cond, bar) do { unsigned _sp = 0; while (cond) { __builtin_amdgcn_s_sleep(1); \
;     if ((++_sp & 255u) == 0u) { if (xb_ld(&(bar)[XB_TMO])) break; if (_sp > XB_SPIN_CAP) { atomicAdd(&(bar)[XB_TMO], 1u); break; } } } } while (0)
; __device__ __forceinline__ void xcd_barrier(const XcdBarrier& b) {
;     ...
;             else XB_SPIN(xb_ld(&bar[XB_TOPGEN]) == tg, bar);
;             __builtin_amdgcn_fence(__ATOMIC_ACQUIRE, "agent");
;             xb_add(&bar[XB_XGEN(b.x)], 1u);
;             asm volatile("s_waitcnt vmcnt(0)" ::: "memory");
.LBB0_631:
	s_or_b64 exec, exec, s[10:11]
	s_waitcnt vmcnt(0)
	s_waitcnt vmcnt(0)

; __device__ __forceinline__ unsigned xb_ld(unsigned* p)              { return __hip_atomic_load(p, __ATOMIC_RELAXED, __HIP_MEMORY_SCOPE_AGENT); }
; __device__ __forceinline__ unsigned xb_add(unsigned* p, unsigned v) { return __hip_atomic_fetch_add(p, v, __ATOMIC_RELAXED, __HIP_MEMORY_SCOPE_AGENT); }
; #define XB_SPIN(cond, bar) do { unsigned _sp = 0; while (cond) { __builtin_amdgcn_s_sleep(1); \
;     if ((++_sp & 255u) == 0u) { if (xb_ld(&(bar)[XB_TMO])) break; if (_sp > XB_SPIN_CAP) { atomicAdd(&(bar)[XB_TMO], 1u); break; } } } } while (0)
; __device__ __forceinline__ void xcd_barrier(const XcdBarrier& b) {
;     ...
;         const unsigned old = xb_add(&bar[XB_XSUB(b.x)], 1u);
;         const unsigned gen = old / nloc;
;         if (old + 1u == (gen + 1u) * nloc) {
;             __builtin_amdgcn_fence(__ATOMIC_RELEASE, "agent");
;             asm volatile("s_waitcnt vmcnt(0)" ::: "memory");
;             const unsigned og = xb_add(&bar[XB_TOP], 1u);
;             const unsigned tg = og / nx;
;             if (og + 1u == (tg + 1u) * nx) xb_add(&bar[XB_TOPGEN], 1u);
;             else XB_SPIN(xb_ld(&bar[XB_TOPGEN]) == tg, bar);
;             __builtin_amdgcn_fence(__ATOMIC_ACQUIRE, "agent");
.LBB0_635:
	s_or_b64 exec, exec, s[10:11]
	buffer_inv sc1
	v_cvt_f32_u32_e32 v3, v0
	s_waitcnt vmcnt(0)
	v_readfirstlane_b32 s2, v2
	s_add_u32 s10, s88, 0x803500
	s_addc_u32 s11, s89, 0
	v_rcp_iflag_f32_e32 v3, v3
	v_add_u32_e32 v1, s2, v1
	v_add_u32_e32 v4, 1, v1
	s_mov_b64 s[12:13], -1
	v_mul_f32_e32 v2, 0x4f7ffffe, v3
	v_cvt_u32_f32_e32 v2, v2
	v_sub_u32_e32 v3, 0, v0
	v_mul_lo_u32 v3, v3, v2
	v_mul_hi_u32 v3, v2, v3
	v_add_u32_e32 v2, v2, v3
	v_mul_hi_u32 v2, v1, v2
	v_mul_lo_u32 v3, v2, v0
	v_sub_u32_e32 v1, v1, v3
	v_add_u32_e32 v5, 1, v2
	v_cmp_ge_u32_e32 vcc, v1, v0
	v_sub_u32_e32 v3, v1, v0
	s_nop 0
	v_cndmask_b32_e32 v2, v2, v5, vcc
	v_cndmask_b32_e32 v1, v1, v3, vcc
	v_add_u32_e32 v3, 1, v2
	v_cmp_ge_u32_e32 vcc, v1, v0
	s_nop 1
	v_cndmask_b32_e32 v2, v2, v3, vcc
	v_mul_lo_u32 v1, v0, v2
	v_add_u32_e32 v0, v1, v0
	v_cmp_ne_u32_e32 vcc, v4, v0
	v_mov_b64_e32 v[0:1], s[10:11]
	s_and_saveexec_b64 s[8:9], vcc
	s_cbranch_execz .LBB0_647
	v_mov_b32_e32 v0, 0
	global_load_dword v1, v0, s[10:11] sc1
	s_mov_b64 s[16:17], 0
	s_waitcnt vmcnt(0)
	v_cmp_eq_u32_e32 vcc, v1, v2
	s_and_saveexec_b64 s[14:15], vcc
	s_cbranch_execz .LBB0_646
	s_add_u32 s12, s88, 0x800200
	s_addc_u32 s13, s89, 0
	s_mov_b32 s2, 1
	s_branch .LBB0_639

; __device__ __forceinline__ unsigned xb_add(unsigned* p, unsigned v) { return __hip_atomic_fetch_add(p, v, __ATOMIC_RELAXED, __HIP_MEMORY_SCOPE_AGENT); }
; __device__ __forceinline__ void xcd_barrier(const XcdBarrier& b) {
;     ...
;             __builtin_amdgcn_fence(__ATOMIC_ACQUIRE, "agent");
;             xb_add(&bar[XB_XGEN(b.x)], 1u);
;             asm volatile("s_waitcnt vmcnt(0)" ::: "memory");
.LBB0_649:
	s_or_b64 exec, exec, s[8:9]
	s_mov_b64 s[8:9], exec
	v_mbcnt_lo_u32_b32 v0, s8, 0
	v_mbcnt_hi_u32_b32 v0, s9, v0
	v_cmp_eq_u32_e32 vcc, 0, v0
	s_waitcnt vmcnt(0)
	s_and_saveexec_b64 s[10:11], vcc
	s_cbranch_execz .LBB0_651
	s_bcnt1_i32_b64 s2, s[8:9]
	v_mov_b32_e32 v0, 0x2000
	v_mov_b32_e32 v1, s2

; __device__ __forceinline__ unsigned xb_ld(unsigned* p)              { return __hip_atomic_load(p, __ATOMIC_RELAXED, __HIP_MEMORY_SCOPE_AGENT); }
; __device__ __forceinline__ unsigned xb_add(unsigned* p, unsigned v) { return __hip_atomic_fetch_add(p, v, __ATOMIC_RELAXED, __HIP_MEMORY_SCOPE_AGENT); }
; #define XB_SPIN(cond, bar) do { unsigned _sp = 0; while (cond) { __builtin_amdgcn_s_sleep(1); \
;     if ((++_sp & 255u) == 0u) { if (xb_ld(&(bar)[XB_TMO])) break; if (_sp > XB_SPIN_CAP) { atomicAdd(&(bar)[XB_TMO], 1u); break; } } } } while (0)
; __device__ __forceinline__ void xcd_barrier(const XcdBarrier& b) {
;     ...
;         const unsigned old = xb_add(&bar[XB_XSUB(b.x)], 1u);
;         const unsigned gen = old / nloc;
;         if (old + 1u == (gen + 1u) * nloc) {
;             __builtin_amdgcn_fence(__ATOMIC_RELEASE, "agent");
;             asm volatile("s_waitcnt vmcnt(0)" ::: "memory");
;             const unsigned og = xb_add(&bar[XB_TOP], 1u);
;             const unsigned tg = og / nx;
;             if (og + 1u == (tg + 1u) * nx) xb_add(&bar[XB_TOPGEN], 1u);
;             else XB_SPIN(xb_ld(&bar[XB_TOPGEN]) == tg, bar);
;             __builtin_amdgcn_fence(__ATOMIC_ACQUIRE, "agent");
.LBB0_705:
	s_or_b64 exec, exec, s[24:25]
	v_cvt_f32_u32_e32 v4, v2
	s_waitcnt vmcnt(0)
	v_readfirstlane_b32 s2, v3
	v_sub_u32_e32 v3, 0, v2
	v_rcp_iflag_f32_e32 v4, v4
	v_add_u32_e32 v5, s2, v1
	v_mul_f32_e32 v4, 0x4f7ffffe, v4
	v_cvt_u32_f32_e32 v4, v4
	v_mul_lo_u32 v1, v3, v4
	v_mul_hi_u32 v1, v4, v1
	v_add_u32_e32 v1, v4, v1
	v_mul_hi_u32 v1, v5, v1
	v_mul_lo_u32 v3, v1, v2
	v_sub_u32_e32 v3, v5, v3
	v_add_u32_e32 v4, 1, v1
	v_cmp_ge_u32_e32 vcc, v3, v2
	s_nop 1
	v_cndmask_b32_e32 v1, v1, v4, vcc
	v_sub_u32_e32 v4, v3, v2
	v_cndmask_b32_e32 v3, v3, v4, vcc
	v_add_u32_e32 v4, 1, v1
	v_cmp_ge_u32_e32 vcc, v3, v2
	v_add_u32_e32 v3, 1, v5
	s_nop 0
	v_cndmask_b32_e32 v1, v1, v4, vcc
	v_mul_lo_u32 v4, v2, v1
	v_add_u32_e32 v2, v4, v2
	v_cmp_ne_u32_e32 vcc, v3, v2
	s_and_saveexec_b64 s[2:3], vcc
	s_xor_b64 s[8:9], exec, s[2:3]
	s_cbranch_execz .LBB0_719
	s_waitcnt lgkmcnt(0)
	v_mov_b32_e32 v0, 0
	s_add_u32 s28, s88, 0x803500
	s_addc_u32 s29, s89, 0
	buffer_inv sc1
	global_load_dword v0, v0, s[28:29] sc1
	s_waitcnt vmcnt(0)
	v_cmp_eq_u32_e32 vcc, v0, v1
	s_and_saveexec_b64 s[24:25], vcc
	s_cbranch_execz .LBB0_718
	s_add_u32 s26, s88, 0x800200
	s_addc_u32 s27, s89, 0
	s_mov_b32 s2, 1
	s_mov_b64 s[30:31], 0
	v_mov_b32_e32 v0, 0
	s_branch .LBB0_709

; __device__ __forceinline__ unsigned xb_ld(unsigned* p)              { return __hip_atomic_load(p, __ATOMIC_RELAXED, __HIP_MEMORY_SCOPE_AGENT); }
; __device__ __forceinline__ unsigned xb_add(unsigned* p, unsigned v) { return __hip_atomic_fetch_add(p, v, __ATOMIC_RELAXED, __HIP_MEMORY_SCOPE_AGENT); }
; #define XB_SPIN(cond, bar) do { unsigned _sp = 0; while (cond) { __builtin_amdgcn_s_sleep(1); \
;     if ((++_sp & 255u) == 0u) { if (xb_ld(&(bar)[XB_TMO])) break; if (_sp > XB_SPIN_CAP) { atomicAdd(&(bar)[XB_TMO], 1u); break; } } } } while (0)
; __device__ __forceinline__ void xcd_barrier(const XcdBarrier& b) {
;     ...
;             else XB_SPIN(xb_ld(&bar[XB_TOPGEN]) == tg, bar);
;             __builtin_amdgcn_fence(__ATOMIC_ACQUIRE, "agent");
;             xb_add(&bar[XB_XGEN(b.x)], 1u);
;             asm volatile("s_waitcnt vmcnt(0)" ::: "memory");
.LBB0_718:
	s_or_b64 exec, exec, s[24:25]
	s_waitcnt vmcnt(0)
	s_waitcnt vmcnt(0)

; __device__ __forceinline__ unsigned xb_ld(unsigned* p)              { return __hip_atomic_load(p, __ATOMIC_RELAXED, __HIP_MEMORY_SCOPE_AGENT); }
; __device__ __forceinline__ unsigned xb_add(unsigned* p, unsigned v) { return __hip_atomic_fetch_add(p, v, __ATOMIC_RELAXED, __HIP_MEMORY_SCOPE_AGENT); }
; #define XB_SPIN(cond, bar) do { unsigned _sp = 0; while (cond) { __builtin_amdgcn_s_sleep(1); \
;     if ((++_sp & 255u) == 0u) { if (xb_ld(&(bar)[XB_TMO])) break; if (_sp > XB_SPIN_CAP) { atomicAdd(&(bar)[XB_TMO], 1u); break; } } } } while (0)
; __device__ __forceinline__ void xcd_barrier(const XcdBarrier& b) {
;     ...
;         const unsigned old = xb_add(&bar[XB_XSUB(b.x)], 1u);
;         const unsigned gen = old / nloc;
;         if (old + 1u == (gen + 1u) * nloc) {
;             __builtin_amdgcn_fence(__ATOMIC_RELEASE, "agent");
;             asm volatile("s_waitcnt vmcnt(0)" ::: "memory");
;             const unsigned og = xb_add(&bar[XB_TOP], 1u);
;             const unsigned tg = og / nx;
;             if (og + 1u == (tg + 1u) * nx) xb_add(&bar[XB_TOPGEN], 1u);
;             else XB_SPIN(xb_ld(&bar[XB_TOPGEN]) == tg, bar);
;             __builtin_amdgcn_fence(__ATOMIC_ACQUIRE, "agent");
.LBB0_722:
	s_or_b64 exec, exec, s[24:25]
	buffer_inv sc1
	v_cvt_f32_u32_e32 v3, v0
	s_waitcnt vmcnt(0)
	v_readfirstlane_b32 s2, v2
	s_add_u32 s24, s88, 0x803500
	s_addc_u32 s25, s89, 0
	v_rcp_iflag_f32_e32 v3, v3
	v_add_u32_e32 v1, s2, v1
	v_add_u32_e32 v4, 1, v1
	s_mov_b64 s[26:27], -1
	v_mul_f32_e32 v2, 0x4f7ffffe, v3
	v_cvt_u32_f32_e32 v2, v2
	v_sub_u32_e32 v3, 0, v0
	v_mul_lo_u32 v3, v3, v2
	v_mul_hi_u32 v3, v2, v3
	v_add_u32_e32 v2, v2, v3
	v_mul_hi_u32 v2, v1, v2
	v_mul_lo_u32 v3, v2, v0
	v_sub_u32_e32 v1, v1, v3
	v_add_u32_e32 v5, 1, v2
	v_cmp_ge_u32_e32 vcc, v1, v0
	v_sub_u32_e32 v3, v1, v0
	s_nop 0
	v_cndmask_b32_e32 v2, v2, v5, vcc
	v_cndmask_b32_e32 v1, v1, v3, vcc
	v_add_u32_e32 v3, 1, v2
	v_cmp_ge_u32_e32 vcc, v1, v0
	s_nop 1
	v_cndmask_b32_e32 v2, v2, v3, vcc
	v_mul_lo_u32 v1, v0, v2
	v_add_u32_e32 v0, v1, v0
	v_cmp_ne_u32_e32 vcc, v4, v0
	v_mov_b64_e32 v[0:1], s[24:25]
	s_and_saveexec_b64 s[8:9], vcc
	s_cbranch_execz .LBB0_734
	v_mov_b32_e32 v0, 0
	global_load_dword v1, v0, s[24:25] sc1
	s_mov_b64 s[30:31], 0
	s_waitcnt vmcnt(0)
	v_cmp_eq_u32_e32 vcc, v1, v2
	s_and_saveexec_b64 s[28:29], vcc
	s_cbranch_execz .LBB0_733
	s_add_u32 s26, s88, 0x800200
	s_addc_u32 s27, s89, 0
	s_mov_b32 s2, 1
	s_branch .LBB0_726

; __device__ __forceinline__ unsigned xb_add(unsigned* p, unsigned v) { return __hip_atomic_fetch_add(p, v, __ATOMIC_RELAXED, __HIP_MEMORY_SCOPE_AGENT); }
; __device__ __forceinline__ void xcd_barrier(const XcdBarrier& b) {
;     ...
;             __builtin_amdgcn_fence(__ATOMIC_ACQUIRE, "agent");
;             xb_add(&bar[XB_XGEN(b.x)], 1u);
;             asm volatile("s_waitcnt vmcnt(0)" ::: "memory");
.LBB0_736:
	s_or_b64 exec, exec, s[8:9]
	s_mov_b64 s[8:9], exec
	v_mbcnt_lo_u32_b32 v0, s8, 0
	v_mbcnt_hi_u32_b32 v0, s9, v0
	v_cmp_eq_u32_e32 vcc, 0, v0
	s_waitcnt vmcnt(0)
	s_and_saveexec_b64 s[24:25], vcc
	s_cbranch_execz .LBB0_738
	s_bcnt1_i32_b64 s2, s[8:9]
	v_mov_b32_e32 v0, 0x2000
	v_mov_b32_e32 v1, s2

; __device__ __forceinline__ unsigned xb_ld(unsigned* p)              { return __hip_atomic_load(p, __ATOMIC_RELAXED, __HIP_MEMORY_SCOPE_AGENT); }
; __device__ __forceinline__ unsigned xb_add(unsigned* p, unsigned v) { return __hip_atomic_fetch_add(p, v, __ATOMIC_RELAXED, __HIP_MEMORY_SCOPE_AGENT); }
; #define XB_SPIN(cond, bar) do { unsigned _sp = 0; while (cond) { __builtin_amdgcn_s_sleep(1); \
;     if ((++_sp & 255u) == 0u) { if (xb_ld(&(bar)[XB_TMO])) break; if (_sp > XB_SPIN_CAP) { atomicAdd(&(bar)[XB_TMO], 1u); break; } } } } while (0)
; __device__ __forceinline__ void xcd_barrier(const XcdBarrier& b) {
;     ...
;         const unsigned old = xb_add(&bar[XB_XSUB(b.x)], 1u);
;         const unsigned gen = old / nloc;
;         if (old + 1u == (gen + 1u) * nloc) {
;             __builtin_amdgcn_fence(__ATOMIC_RELEASE, "agent");
;             asm volatile("s_waitcnt vmcnt(0)" ::: "memory");
;             const unsigned og = xb_add(&bar[XB_TOP], 1u);
;             const unsigned tg = og / nx;
;             if (og + 1u == (tg + 1u) * nx) xb_add(&bar[XB_TOPGEN], 1u);
;             else XB_SPIN(xb_ld(&bar[XB_TOPGEN]) == tg, bar);
;             __builtin_amdgcn_fence(__ATOMIC_ACQUIRE, "agent");
.LBB0_830:
	s_or_b64 exec, exec, s[8:9]
	v_cvt_f32_u32_e32 v4, v2
	s_waitcnt vmcnt(0)
	v_readfirstlane_b32 s6, v3
	v_sub_u32_e32 v3, 0, v2
	v_rcp_iflag_f32_e32 v4, v4
	v_add_u32_e32 v5, s6, v1
	v_mul_f32_e32 v4, 0x4f7ffffe, v4
	v_cvt_u32_f32_e32 v4, v4
	v_mul_lo_u32 v1, v3, v4
	v_mul_hi_u32 v1, v4, v1
	v_add_u32_e32 v1, v4, v1
	v_mul_hi_u32 v1, v5, v1
	v_mul_lo_u32 v3, v1, v2
	v_sub_u32_e32 v3, v5, v3
	v_add_u32_e32 v4, 1, v1
	v_cmp_ge_u32_e32 vcc, v3, v2
	s_nop 1
	v_cndmask_b32_e32 v1, v1, v4, vcc
	v_sub_u32_e32 v4, v3, v2
	v_cndmask_b32_e32 v3, v3, v4, vcc
	v_add_u32_e32 v4, 1, v1
	v_cmp_ge_u32_e32 vcc, v3, v2
	v_add_u32_e32 v3, 1, v5
	s_nop 0
	v_cndmask_b32_e32 v1, v1, v4, vcc
	v_mul_lo_u32 v4, v2, v1
	v_add_u32_e32 v2, v4, v2
	v_cmp_ne_u32_e32 vcc, v3, v2
	s_and_saveexec_b64 s[6:7], vcc
	s_xor_b64 s[6:7], exec, s[6:7]
	s_cbranch_execz .LBB0_844
	s_waitcnt lgkmcnt(0)
	v_mov_b32_e32 v0, 0
	s_add_u32 s16, s88, 0x803500
	s_addc_u32 s17, s89, 0
	buffer_inv sc1
	global_load_dword v0, v0, s[16:17] sc1
	s_waitcnt vmcnt(0)
	v_cmp_eq_u32_e32 vcc, v0, v1
	s_and_saveexec_b64 s[8:9], vcc
	s_cbranch_execz .LBB0_843
	s_add_u32 s14, s88, 0x800200
	s_addc_u32 s15, s89, 0
	s_mov_b32 s28, 1
	s_mov_b64 s[18:19], 0
	v_mov_b32_e32 v0, 0
	s_branch .LBB0_834

; __device__ __forceinline__ unsigned xb_ld(unsigned* p)              { return __hip_atomic_load(p, __ATOMIC_RELAXED, __HIP_MEMORY_SCOPE_AGENT); }
; __device__ __forceinline__ unsigned xb_add(unsigned* p, unsigned v) { return __hip_atomic_fetch_add(p, v, __ATOMIC_RELAXED, __HIP_MEMORY_SCOPE_AGENT); }
; #define XB_SPIN(cond, bar) do { unsigned _sp = 0; while (cond) { __builtin_amdgcn_s_sleep(1); \
;     if ((++_sp & 255u) == 0u) { if (xb_ld(&(bar)[XB_TMO])) break; if (_sp > XB_SPIN_CAP) { atomicAdd(&(bar)[XB_TMO], 1u); break; } } } } while (0)
; __device__ __forceinline__ void xcd_barrier(const XcdBarrier& b) {
;     ...
;         const unsigned old = xb_add(&bar[XB_XSUB(b.x)], 1u);
;         const unsigned gen = old / nloc;
;         if (old + 1u == (gen + 1u) * nloc) {
;             __builtin_amdgcn_fence(__ATOMIC_RELEASE, "agent");
;             asm volatile("s_waitcnt vmcnt(0)" ::: "memory");
;             const unsigned og = xb_add(&bar[XB_TOP], 1u);
;             const unsigned tg = og / nx;
;             if (og + 1u == (tg + 1u) * nx) xb_add(&bar[XB_TOPGEN], 1u);
;             else XB_SPIN(xb_ld(&bar[XB_TOPGEN]) == tg, bar);
;             __builtin_amdgcn_fence(__ATOMIC_ACQUIRE, "agent");
.LBB0_847:
	s_or_b64 exec, exec, s[8:9]
	buffer_inv sc1
	v_cvt_f32_u32_e32 v3, v0
	s_waitcnt vmcnt(0)
	v_readfirstlane_b32 s6, v2
	s_add_u32 s8, s88, 0x803500
	s_addc_u32 s9, s89, 0
	v_rcp_iflag_f32_e32 v3, v3
	v_add_u32_e32 v1, s6, v1
	v_add_u32_e32 v4, 1, v1
	s_mov_b64 s[14:15], -1
	v_mul_f32_e32 v2, 0x4f7ffffe, v3
	v_cvt_u32_f32_e32 v2, v2
	v_sub_u32_e32 v3, 0, v0
	v_mul_lo_u32 v3, v3, v2
	v_mul_hi_u32 v3, v2, v3
	v_add_u32_e32 v2, v2, v3
	v_mul_hi_u32 v2, v1, v2
	v_mul_lo_u32 v3, v2, v0
	v_sub_u32_e32 v1, v1, v3
	v_add_u32_e32 v5, 1, v2
	v_cmp_ge_u32_e32 vcc, v1, v0
	v_sub_u32_e32 v3, v1, v0
	s_nop 0
	v_cndmask_b32_e32 v2, v2, v5, vcc
	v_cndmask_b32_e32 v1, v1, v3, vcc
	v_add_u32_e32 v3, 1, v2
	v_cmp_ge_u32_e32 vcc, v1, v0
	s_nop 1
	v_cndmask_b32_e32 v2, v2, v3, vcc
	v_mul_lo_u32 v1, v0, v2
	v_add_u32_e32 v0, v1, v0
	v_cmp_ne_u32_e32 vcc, v4, v0
	v_mov_b64_e32 v[0:1], s[8:9]
	s_and_saveexec_b64 s[6:7], vcc
	s_cbranch_execz .LBB0_859
	v_mov_b32_e32 v0, 0
	global_load_dword v1, v0, s[8:9] sc1
	s_mov_b64 s[18:19], 0
	s_waitcnt vmcnt(0)
	v_cmp_eq_u32_e32 vcc, v1, v2
	s_and_saveexec_b64 s[16:17], vcc
	s_cbranch_execz .LBB0_858
	s_add_u32 s14, s88, 0x800200
	s_addc_u32 s15, s89, 0
	s_mov_b32 s28, 1
	s_branch .LBB0_851

; __device__ __forceinline__ unsigned xb_ld(unsigned* p)              { return __hip_atomic_load(p, __ATOMIC_RELAXED, __HIP_MEMORY_SCOPE_AGENT); }
; __device__ __forceinline__ unsigned xb_add(unsigned* p, unsigned v) { return __hip_atomic_fetch_add(p, v, __ATOMIC_RELAXED, __HIP_MEMORY_SCOPE_AGENT); }
; #define XB_SPIN(cond, bar) do { unsigned _sp = 0; while (cond) { __builtin_amdgcn_s_sleep(1); \
;     if ((++_sp & 255u) == 0u) { if (xb_ld(&(bar)[XB_TMO])) break; if (_sp > XB_SPIN_CAP) { atomicAdd(&(bar)[XB_TMO], 1u); break; } } } } while (0)
; __device__ __forceinline__ void xcd_barrier(const XcdBarrier& b) {
;     ...
;         const unsigned old = xb_add(&bar[XB_XSUB(b.x)], 1u);
;         const unsigned gen = old / nloc;
;         if (old + 1u == (gen + 1u) * nloc) {
;             __builtin_amdgcn_fence(__ATOMIC_RELEASE, "agent");
;             asm volatile("s_waitcnt vmcnt(0)" ::: "memory");
;             const unsigned og = xb_add(&bar[XB_TOP], 1u);
;             const unsigned tg = og / nx;
;             if (og + 1u == (tg + 1u) * nx) xb_add(&bar[XB_TOPGEN], 1u);
;             else XB_SPIN(xb_ld(&bar[XB_TOPGEN]) == tg, bar);
;             __builtin_amdgcn_fence(__ATOMIC_ACQUIRE, "agent");
.LBB0_909:
	s_or_b64 exec, exec, s[8:9]
	v_cvt_f32_u32_e32 v4, v2
	s_waitcnt vmcnt(0)
	v_readfirstlane_b32 s6, v3
	v_sub_u32_e32 v3, 0, v2
	v_rcp_iflag_f32_e32 v4, v4
	v_add_u32_e32 v5, s6, v1
	v_mul_f32_e32 v4, 0x4f7ffffe, v4
	v_cvt_u32_f32_e32 v4, v4
	v_mul_lo_u32 v1, v3, v4
	v_mul_hi_u32 v1, v4, v1
	v_add_u32_e32 v1, v4, v1
	v_mul_hi_u32 v1, v5, v1
	v_mul_lo_u32 v3, v1, v2
	v_sub_u32_e32 v3, v5, v3
	v_add_u32_e32 v4, 1, v1
	v_cmp_ge_u32_e32 vcc, v3, v2
	s_nop 1
	v_cndmask_b32_e32 v1, v1, v4, vcc
	v_sub_u32_e32 v4, v3, v2
	v_cndmask_b32_e32 v3, v3, v4, vcc
	v_add_u32_e32 v4, 1, v1
	v_cmp_ge_u32_e32 vcc, v3, v2
	v_add_u32_e32 v3, 1, v5
	s_nop 0
	v_cndmask_b32_e32 v1, v1, v4, vcc
	v_mul_lo_u32 v4, v2, v1
	v_add_u32_e32 v2, v4, v2
	v_cmp_ne_u32_e32 vcc, v3, v2
	s_and_saveexec_b64 s[6:7], vcc
	s_xor_b64 s[6:7], exec, s[6:7]
	s_cbranch_execz .LBB0_923
	s_waitcnt lgkmcnt(0)
	v_mov_b32_e32 v0, 0
	s_add_u32 s14, s88, 0x803500
	s_addc_u32 s15, s89, 0
	buffer_inv sc1
	global_load_dword v0, v0, s[14:15] sc1
	s_waitcnt vmcnt(0)
	v_cmp_eq_u32_e32 vcc, v0, v1
	s_and_saveexec_b64 s[8:9], vcc
	s_cbranch_execz .LBB0_922
	s_add_u32 s12, s88, 0x800200
	s_addc_u32 s13, s89, 0
	s_mov_b32 s26, 1
	s_mov_b64 s[16:17], 0
	v_mov_b32_e32 v0, 0
	s_branch .LBB0_913

; __device__ __forceinline__ unsigned xb_ld(unsigned* p)              { return __hip_atomic_load(p, __ATOMIC_RELAXED, __HIP_MEMORY_SCOPE_AGENT); }
; __device__ __forceinline__ unsigned xb_add(unsigned* p, unsigned v) { return __hip_atomic_fetch_add(p, v, __ATOMIC_RELAXED, __HIP_MEMORY_SCOPE_AGENT); }
; #define XB_SPIN(cond, bar) do { unsigned _sp = 0; while (cond) { __builtin_amdgcn_s_sleep(1); \
;     if ((++_sp & 255u) == 0u) { if (xb_ld(&(bar)[XB_TMO])) break; if (_sp > XB_SPIN_CAP) { atomicAdd(&(bar)[XB_TMO], 1u); break; } } } } while (0)
; __device__ __forceinline__ void xcd_barrier(const XcdBarrier& b) {
;     ...
;         const unsigned old = xb_add(&bar[XB_XSUB(b.x)], 1u);
;         const unsigned gen = old / nloc;
;         if (old + 1u == (gen + 1u) * nloc) {
;             __builtin_amdgcn_fence(__ATOMIC_RELEASE, "agent");
;             asm volatile("s_waitcnt vmcnt(0)" ::: "memory");
;             const unsigned og = xb_add(&bar[XB_TOP], 1u);
;             const unsigned tg = og / nx;
;             if (og + 1u == (tg + 1u) * nx) xb_add(&bar[XB_TOPGEN], 1u);
;             else XB_SPIN(xb_ld(&bar[XB_TOPGEN]) == tg, bar);
;             __builtin_amdgcn_fence(__ATOMIC_ACQUIRE, "agent");
.LBB0_926:
	s_or_b64 exec, exec, s[8:9]
	buffer_inv sc1
	v_cvt_f32_u32_e32 v3, v0
	s_waitcnt vmcnt(0)
	v_readfirstlane_b32 s6, v2
	s_add_u32 s8, s88, 0x803500
	s_addc_u32 s9, s89, 0
	v_rcp_iflag_f32_e32 v3, v3
	v_add_u32_e32 v1, s6, v1
	v_add_u32_e32 v4, 1, v1
	s_mov_b64 s[12:13], -1
	v_mul_f32_e32 v2, 0x4f7ffffe, v3
	v_cvt_u32_f32_e32 v2, v2
	v_sub_u32_e32 v3, 0, v0
	v_mul_lo_u32 v3, v3, v2
	v_mul_hi_u32 v3, v2, v3
	v_add_u32_e32 v2, v2, v3
	v_mul_hi_u32 v2, v1, v2
	v_mul_lo_u32 v3, v2, v0
	v_sub_u32_e32 v1, v1, v3
	v_add_u32_e32 v5, 1, v2
	v_cmp_ge_u32_e32 vcc, v1, v0
	v_sub_u32_e32 v3, v1, v0
	s_nop 0
	v_cndmask_b32_e32 v2, v2, v5, vcc
	v_cndmask_b32_e32 v1, v1, v3, vcc
	v_add_u32_e32 v3, 1, v2
	v_cmp_ge_u32_e32 vcc, v1, v0
	s_nop 1
	v_cndmask_b32_e32 v2, v2, v3, vcc
	v_mul_lo_u32 v1, v0, v2
	v_add_u32_e32 v0, v1, v0
	v_cmp_ne_u32_e32 vcc, v4, v0
	v_mov_b64_e32 v[0:1], s[8:9]
	s_and_saveexec_b64 s[6:7], vcc
	s_cbranch_execz .LBB0_938
	v_mov_b32_e32 v0, 0
	global_load_dword v1, v0, s[8:9] sc1
	s_mov_b64 s[16:17], 0
	s_waitcnt vmcnt(0)
	v_cmp_eq_u32_e32 vcc, v1, v2
	s_and_saveexec_b64 s[14:15], vcc
	s_cbranch_execz .LBB0_937
	s_add_u32 s12, s88, 0x800200
	s_addc_u32 s13, s89, 0
	s_mov_b32 s26, 1
	s_branch .LBB0_930

; __device__ __forceinline__ unsigned xb_ld(unsigned* p)              { return __hip_atomic_load(p, __ATOMIC_RELAXED, __HIP_MEMORY_SCOPE_AGENT); }
; __device__ __forceinline__ unsigned xb_add(unsigned* p, unsigned v) { return __hip_atomic_fetch_add(p, v, __ATOMIC_RELAXED, __HIP_MEMORY_SCOPE_AGENT); }
; #define XB_SPIN(cond, bar) do { unsigned _sp = 0; while (cond) { __builtin_amdgcn_s_sleep(1); \
;     if ((++_sp & 255u) == 0u) { if (xb_ld(&(bar)[XB_TMO])) break; if (_sp > XB_SPIN_CAP) { atomicAdd(&(bar)[XB_TMO], 1u); break; } } } } while (0)
; __device__ __forceinline__ void xcd_barrier(const XcdBarrier& b) {
;     ...
;         const unsigned old = xb_add(&bar[XB_XSUB(b.x)], 1u);
;         const unsigned gen = old / nloc;
;         if (old + 1u == (gen + 1u) * nloc) {
;             __builtin_amdgcn_fence(__ATOMIC_RELEASE, "agent");
;             asm volatile("s_waitcnt vmcnt(0)" ::: "memory");
;             const unsigned og = xb_add(&bar[XB_TOP], 1u);
;             const unsigned tg = og / nx;
;             if (og + 1u == (tg + 1u) * nx) xb_add(&bar[XB_TOPGEN], 1u);
;             else XB_SPIN(xb_ld(&bar[XB_TOPGEN]) == tg, bar);
;             __builtin_amdgcn_fence(__ATOMIC_ACQUIRE, "agent");
.LBB0_1006:
	s_or_b64 exec, exec, s[8:9]
	v_cvt_f32_u32_e32 v4, v2
	s_waitcnt vmcnt(0)
	v_readfirstlane_b32 s6, v3
	v_sub_u32_e32 v3, 0, v2
	v_rcp_iflag_f32_e32 v4, v4
	v_add_u32_e32 v5, s6, v1
	v_mul_f32_e32 v4, 0x4f7ffffe, v4
	v_cvt_u32_f32_e32 v4, v4
	v_mul_lo_u32 v1, v3, v4
	v_mul_hi_u32 v1, v4, v1
	v_add_u32_e32 v1, v4, v1
	v_mul_hi_u32 v1, v5, v1
	v_mul_lo_u32 v3, v1, v2
	v_sub_u32_e32 v3, v5, v3
	v_add_u32_e32 v4, 1, v1
	v_cmp_ge_u32_e32 vcc, v3, v2
	s_nop 1
	v_cndmask_b32_e32 v1, v1, v4, vcc
	v_sub_u32_e32 v4, v3, v2
	v_cndmask_b32_e32 v3, v3, v4, vcc
	v_add_u32_e32 v4, 1, v1
	v_cmp_ge_u32_e32 vcc, v3, v2
	v_add_u32_e32 v3, 1, v5
	s_nop 0
	v_cndmask_b32_e32 v1, v1, v4, vcc
	v_mul_lo_u32 v4, v2, v1
	v_add_u32_e32 v2, v4, v2
	v_cmp_ne_u32_e32 vcc, v3, v2
	s_and_saveexec_b64 s[6:7], vcc
	s_xor_b64 s[6:7], exec, s[6:7]
	s_cbranch_execz .LBB0_1020
	s_waitcnt lgkmcnt(0)
	v_mov_b32_e32 v0, 0
	s_add_u32 s12, s88, 0x803500
	s_addc_u32 s13, s89, 0
	buffer_inv sc1
	global_load_dword v0, v0, s[12:13] sc1
	s_waitcnt vmcnt(0)
	v_cmp_eq_u32_e32 vcc, v0, v1
	s_and_saveexec_b64 s[8:9], vcc
	s_cbranch_execz .LBB0_1019
	s_add_u32 s10, s88, 0x800200
	s_addc_u32 s11, s89, 0
	s_mov_b32 s24, 1
	s_mov_b64 s[14:15], 0
	v_mov_b32_e32 v0, 0
	s_branch .LBB0_1010

; __device__ __forceinline__ unsigned xb_ld(unsigned* p)              { return __hip_atomic_load(p, __ATOMIC_RELAXED, __HIP_MEMORY_SCOPE_AGENT); }
; __device__ __forceinline__ unsigned xb_add(unsigned* p, unsigned v) { return __hip_atomic_fetch_add(p, v, __ATOMIC_RELAXED, __HIP_MEMORY_SCOPE_AGENT); }
; #define XB_SPIN(cond, bar) do { unsigned _sp = 0; while (cond) { __builtin_amdgcn_s_sleep(1); \
;     if ((++_sp & 255u) == 0u) { if (xb_ld(&(bar)[XB_TMO])) break; if (_sp > XB_SPIN_CAP) { atomicAdd(&(bar)[XB_TMO], 1u); break; } } } } while (0)
; __device__ __forceinline__ void xcd_barrier(const XcdBarrier& b) {
;     ...
;         const unsigned old = xb_add(&bar[XB_XSUB(b.x)], 1u);
;         const unsigned gen = old / nloc;
;         if (old + 1u == (gen + 1u) * nloc) {
;             __builtin_amdgcn_fence(__ATOMIC_RELEASE, "agent");
;             asm volatile("s_waitcnt vmcnt(0)" ::: "memory");
;             const unsigned og = xb_add(&bar[XB_TOP], 1u);
;             const unsigned tg = og / nx;
;             if (og + 1u == (tg + 1u) * nx) xb_add(&bar[XB_TOPGEN], 1u);
;             else XB_SPIN(xb_ld(&bar[XB_TOPGEN]) == tg, bar);
;             __builtin_amdgcn_fence(__ATOMIC_ACQUIRE, "agent");
.LBB0_1023:
	s_or_b64 exec, exec, s[8:9]
	buffer_inv sc1
	v_cvt_f32_u32_e32 v3, v0
	s_waitcnt vmcnt(0)
	v_readfirstlane_b32 s6, v2
	s_add_u32 s8, s88, 0x803500
	s_addc_u32 s9, s89, 0
	v_rcp_iflag_f32_e32 v3, v3
	v_add_u32_e32 v1, s6, v1
	v_add_u32_e32 v4, 1, v1
	s_mov_b64 s[10:11], -1
	v_mul_f32_e32 v2, 0x4f7ffffe, v3
	v_cvt_u32_f32_e32 v2, v2
	v_sub_u32_e32 v3, 0, v0
	v_mul_lo_u32 v3, v3, v2
	v_mul_hi_u32 v3, v2, v3
	v_add_u32_e32 v2, v2, v3
	v_mul_hi_u32 v2, v1, v2
	v_mul_lo_u32 v3, v2, v0
	v_sub_u32_e32 v1, v1, v3
	v_add_u32_e32 v5, 1, v2
	v_cmp_ge_u32_e32 vcc, v1, v0
	v_sub_u32_e32 v3, v1, v0
	s_nop 0
	v_cndmask_b32_e32 v2, v2, v5, vcc
	v_cndmask_b32_e32 v1, v1, v3, vcc
	v_add_u32_e32 v3, 1, v2
	v_cmp_ge_u32_e32 vcc, v1, v0
	s_nop 1
	v_cndmask_b32_e32 v2, v2, v3, vcc
	v_mul_lo_u32 v1, v0, v2
	v_add_u32_e32 v0, v1, v0
	v_cmp_ne_u32_e32 vcc, v4, v0
	v_mov_b64_e32 v[0:1], s[8:9]
	s_and_saveexec_b64 s[6:7], vcc
	s_cbranch_execz .LBB0_1035
	v_mov_b32_e32 v0, 0
	global_load_dword v1, v0, s[8:9] sc1
	s_mov_b64 s[14:15], 0
	s_waitcnt vmcnt(0)
	v_cmp_eq_u32_e32 vcc, v1, v2
	s_and_saveexec_b64 s[12:13], vcc
	s_cbranch_execz .LBB0_1034
	s_add_u32 s10, s88, 0x800200
	s_addc_u32 s11, s89, 0
	s_mov_b32 s24, 1
	s_branch .LBB0_1027
